# merge-GEMM epilogue: second half's 8 gate loads issued with the first half's (dead fragment registers)
# baseline (speedup 1.0000x reference)
; __device__ __forceinline__ int opaque_tid() { int t = threadIdx.x; asm volatile("" : "+v"(t)); return t; }
; __device__ __forceinline__ size_t g8_off(int row, int colg) { return ((size_t)(row >> 4) * 128 + (colg >> 5)) * 512 + (row & 15) * 32 + (colg & 31); }
;     __device__ __forceinline__ void operator()(const f32x4 (&acc)[2][2][4][2], const Unit& u, int wr, int wc, int fr, int fq) const {
;         { const int t_ = opaque_tid(); wr = t_ >> 8; wc = (t_ >> 6) & 3; fr = t_ & 15; fq = (t_ >> 4) & 3; }
;         const int row0 = u.pm * 256 + wr * 64 + fr, c0 = u.pn * 256 + wc * 32 + 8 * fq;
; #pragma unroll
;         for (int ai = 0; ai < 2; ++ai) {
;             u32x2 gq[4][2];
; #pragma unroll
;             for (int m = 0; m < 4; ++m)
; #pragma unroll
;                 for (int bj = 0; bj < 2; ++bj) gq[m][bj] = *(const u32x2*)(G8 + g8_off(row0 + ai * 128 + m * 16, 3 * 1024 + c0 + bj * 128));
.LBB0_40:
	v_mov_b32_e32 v1, v189
	v_mov_b32_e32 v147, v0
	v_ashrrev_i32_e32 v2, 2, v1
	v_and_b32_e32 v3, 15, v1
	v_and_b32_e32 v2, 0xffffffc0, v2
	v_lshrrev_b32_e32 v1, 1, v1
	v_add_u32_e32 v145, s13, v2
	v_and_b32_e32 v2, 0x78, v1
	v_or_b32_e32 v2, s11, v2
	v_lshlrev_b32_e32 v146, 5, v3
	v_add_u32_e32 v150, 0xc00, v2
	v_and_b32_e32 v148, 24, v1
	v_mov_b32_e32 v149, v0
	v_lshl_add_u64 v[146:147], s[6:7], 0, v[146:147]
	v_lshl_add_u64 v[146:147], v[146:147], 0, v[148:149]
	v_ashrrev_i32_e32 v148, 5, v150
	v_ashrrev_i32_e32 v150, 4, v145
	v_ashrrev_i32_e32 v151, 31, v150
	v_ashrrev_i32_e32 v149, 31, v148
	v_lshlrev_b64 v[150:151], 16, v[150:151]
	v_lshlrev_b64 v[148:149], 9, v[148:149]
	v_lshl_add_u64 v[152:153], v[146:147], 0, v[150:151]
	v_lshl_add_u64 v[150:151], v[152:153], 0, v[148:149]
	global_load_dwordx2 v[172:173], v[150:151], off
	v_add_u32_e32 v1, 0xc80, v2
	v_ashrrev_i32_e32 v150, 5, v1
	v_ashrrev_i32_e32 v151, 31, v150
	v_lshlrev_b64 v[150:151], 9, v[150:151]
	v_lshl_add_u64 v[152:153], v[152:153], 0, v[150:151]
	global_load_dwordx2 v[170:171], v[152:153], off
	v_or_b32_e32 v144, v145, v3
	v_or_b32_e32 v168, 16, v144
	v_ashrrev_i32_e32 v152, 4, v168
	v_ashrrev_i32_e32 v153, 31, v152
	v_lshlrev_b64 v[152:153], 16, v[152:153]
	v_lshl_add_u64 v[152:153], v[146:147], 0, v[152:153]
	v_lshl_add_u64 v[154:155], v[152:153], 0, v[148:149]
	global_load_dwordx2 v[166:167], v[154:155], off
	v_lshl_add_u64 v[152:153], v[152:153], 0, v[150:151]
	global_load_dwordx2 v[164:165], v[152:153], off
	v_or_b32_e32 v162, 32, v144
	v_ashrrev_i32_e32 v152, 4, v162
	v_ashrrev_i32_e32 v153, 31, v152
	v_lshlrev_b64 v[152:153], 16, v[152:153]
	v_lshl_add_u64 v[152:153], v[146:147], 0, v[152:153]
	v_lshl_add_u64 v[154:155], v[152:153], 0, v[148:149]
	global_load_dwordx2 v[160:161], v[154:155], off
	v_lshl_add_u64 v[152:153], v[152:153], 0, v[150:151]
	global_load_dwordx2 v[158:159], v[152:153], off
	v_or_b32_e32 v156, 48, v144
	v_ashrrev_i32_e32 v152, 4, v156
	v_ashrrev_i32_e32 v153, 31, v152
	v_lshlrev_b64 v[152:153], 16, v[152:153]
	v_lshl_add_u64 v[152:153], v[146:147], 0, v[152:153]
	v_lshl_add_u64 v[154:155], v[152:153], 0, v[148:149]
	global_load_dwordx2 v[154:155], v[154:155], off
	v_ashrrev_i32_e32 v145, 31, v144
	v_lshlrev_b64 v[174:175], 11, v[144:145]
	v_ashrrev_i32_e32 v3, 31, v2
	v_lshlrev_b64 v[2:3], 1, v[2:3]
	v_lshl_add_u64 v[152:153], v[152:153], 0, v[150:151]
	global_load_dwordx2 v[152:153], v[152:153], off
	v_ashrrev_i32_e32 v169, 31, v168
	v_ashrrev_i32_e32 v163, 31, v162
	v_ashrrev_i32_e32 v157, 31, v156
	v_add_u32_e32 v200, 0x80, v144
	s_nop 0
	v_ashrrev_i32_e32 v202, 4, v200
	v_ashrrev_i32_e32 v203, 31, v202
	v_lshlrev_b64 v[202:203], 16, v[202:203]
	v_lshl_add_u64 v[202:203], v[146:147], 0, v[202:203]
	v_lshl_add_u64 v[204:205], v[202:203], 0, v[148:149]
	global_load_dwordx2 v[206:207], v[204:205], off
	v_lshl_add_u64 v[202:203], v[202:203], 0, v[150:151]
	global_load_dwordx2 v[208:209], v[202:203], off
	v_add_u32_e32 v210, 0x90, v144
	v_ashrrev_i32_e32 v202, 4, v210
	v_ashrrev_i32_e32 v203, 31, v202
	v_lshlrev_b64 v[202:203], 16, v[202:203]
	v_lshl_add_u64 v[202:203], v[146:147], 0, v[202:203]
	v_lshl_add_u64 v[204:205], v[202:203], 0, v[148:149]
	global_load_dwordx2 v[212:213], v[204:205], off
	v_lshl_add_u64 v[202:203], v[202:203], 0, v[150:151]
	global_load_dwordx2 v[214:215], v[202:203], off
	v_add_u32_e32 v222, 0xa0, v144
	v_ashrrev_i32_e32 v202, 4, v222
	v_ashrrev_i32_e32 v203, 31, v202
	v_lshlrev_b64 v[202:203], 16, v[202:203]
	v_lshl_add_u64 v[202:203], v[146:147], 0, v[202:203]
	v_lshl_add_u64 v[204:205], v[202:203], 0, v[148:149]
	global_load_dwordx2 v[224:225], v[204:205], off
	v_lshl_add_u64 v[202:203], v[202:203], 0, v[150:151]
	global_load_dwordx2 v[204:205], v[202:203], off
	v_add_u32_e32 v226, 0xb0, v144
	v_ashrrev_i32_e32 v202, 4, v226
	v_ashrrev_i32_e32 v203, 31, v202
	v_lshlrev_b64 v[202:203], 16, v[202:203]
	v_lshl_add_u64 v[202:203], v[146:147], 0, v[202:203]
	v_lshl_add_u64 v[228:229], v[202:203], 0, v[148:149]
	global_load_dwordx2 v[228:229], v[228:229], off
	v_ashrrev_i32_e32 v201, 31, v200
	v_lshlrev_b64 v[200:201], 11, v[200:201]
	v_lshl_add_u64 v[202:203], v[202:203], 0, v[150:151]
	global_load_dwordx2 v[202:203], v[202:203], off
	v_ashrrev_i32_e32 v211, 31, v210
	v_ashrrev_i32_e32 v223, 31, v222
	v_ashrrev_i32_e32 v227, 31, v226
	s_waitcnt vmcnt(8)
; __device__ __forceinline__ unsigned cvt_pk_bf16(float lo, float hi) { const f32x2_ v = {lo, hi}; return __builtin_bit_cast(unsigned, __builtin_convertvector(v, bf16x2_)); }
;     __device__ __forceinline__ void operator()(const f32x4 (&acc)[2][2][4][2], const Unit& u, int wr, int wc, int fr, int fq) const {
;     ...
; #pragma unroll
;             for (int m = 0; m < 4; ++m)
; #pragma unroll
;                 for (int bj = 0; bj < 2; ++bj) {
;                     const int row = row0 + ai * 128 + m * 16, c = c0 + bj * 128;
;                     float v[8];
; #pragma unroll
;                     for (int e = 0; e < 8; ++e) { const unsigned q = ((e < 4 ? gq[m][bj].x : gq[m][bj].y) >> (8 * (e & 3))) & 255u; v[e] = ((float)q + 0.5f) * (1.0f / 256.0f) * acc[ai][bj][m][e >> 2][e & 3]; }
;                     u32x4 w; w.x = cvt_pk_bf16(v[0], v[1]); w.y = cvt_pk_bf16(v[2], v[3]); w.z = cvt_pk_bf16(v[4], v[5]); w.w = cvt_pk_bf16(v[6], v[7]);
;                     *(u32x4*)(MG + (size_t)row * 1024 + c) = w;
;                 }
	v_cvt_f32_ubyte1_e32 v177, v172
	v_cvt_f32_ubyte0_e32 v176, v172
	v_pk_add_f32 v[176:177], v[176:177], 0.5 op_sel_hi:[1,0]
	s_nop 0
	v_pk_mul_f32 v[176:177], v[176:177], s[86:87] op_sel_hi:[1,0]
	s_nop 0
	v_pk_mul_f32 v[128:129], v[128:129], v[176:177]
	v_cvt_f32_ubyte3_e32 v177, v172
	v_cvt_f32_ubyte2_e32 v176, v172
	v_pk_add_f32 v[176:177], v[176:177], 0.5 op_sel_hi:[1,0]
	s_nop 0
	v_pk_mul_f32 v[176:177], v[176:177], s[86:87] op_sel_hi:[1,0]
	s_nop 0
	v_pk_mul_f32 v[130:131], v[130:131], v[176:177]
	v_cvt_f32_ubyte1_e32 v177, v173
	v_cvt_f32_ubyte0_e32 v176, v173
	v_pk_add_f32 v[176:177], v[176:177], 0.5 op_sel_hi:[1,0]
	s_nop 0
	v_pk_mul_f32 v[176:177], v[176:177], s[86:87] op_sel_hi:[1,0]
	s_nop 0
	v_pk_mul_f32 v[176:177], v[124:125], v[176:177]
	v_cvt_f32_ubyte3_e32 v125, v173
	v_cvt_f32_ubyte2_e32 v124, v173
	v_pk_add_f32 v[124:125], v[124:125], 0.5 op_sel_hi:[1,0]
	s_nop 0
	v_pk_mul_f32 v[124:125], v[124:125], s[86:87] op_sel_hi:[1,0]
	s_nop 0
	v_pk_mul_f32 v[172:173], v[126:127], v[124:125]
	v_cvt_pk_bf16_f32 v124, v128, v129
	v_lshl_add_u64 v[128:129], s[8:9], 0, v[174:175]
	v_cvt_pk_bf16_f32 v125, v130, v131
	v_cvt_pk_bf16_f32 v126, v176, v177
	v_cvt_pk_bf16_f32 v127, v172, v173
	v_lshl_add_u64 v[128:129], v[128:129], 0, v[2:3]
	global_store_dwordx4 v[128:129], v[124:127], off
	s_nop 1
	v_cvt_f32_ubyte1_e32 v125, v170
	v_cvt_f32_ubyte0_e32 v124, v170
	v_pk_add_f32 v[124:125], v[124:125], 0.5 op_sel_hi:[1,0]
	s_nop 0
	v_pk_mul_f32 v[124:125], v[124:125], s[86:87] op_sel_hi:[1,0]
	s_nop 0
	v_pk_mul_f32 v[120:121], v[120:121], v[124:125]
	v_cvt_f32_ubyte3_e32 v125, v170
	v_cvt_f32_ubyte2_e32 v124, v170
	v_pk_add_f32 v[124:125], v[124:125], 0.5 op_sel_hi:[1,0]
	s_nop 0
	v_pk_mul_f32 v[124:125], v[124:125], s[86:87] op_sel_hi:[1,0]
	s_nop 0
	v_pk_mul_f32 v[122:123], v[122:123], v[124:125]
	v_cvt_f32_ubyte1_e32 v125, v171
	v_cvt_f32_ubyte0_e32 v124, v171
	v_pk_add_f32 v[124:125], v[124:125], 0.5 op_sel_hi:[1,0]
	s_nop 0
	v_pk_mul_f32 v[124:125], v[124:125], s[86:87] op_sel_hi:[1,0]
	s_nop 0
	v_pk_mul_f32 v[124:125], v[116:117], v[124:125]
	v_cvt_f32_ubyte3_e32 v117, v171
	v_cvt_f32_ubyte2_e32 v116, v171
	v_pk_add_f32 v[116:117], v[116:117], 0.5 op_sel_hi:[1,0]
	s_nop 0
	v_pk_mul_f32 v[116:117], v[116:117], s[86:87] op_sel_hi:[1,0]
	s_nop 0
	v_pk_mul_f32 v[126:127], v[118:119], v[116:117]
	v_cvt_pk_bf16_f32 v116, v120, v121
	v_cvt_pk_bf16_f32 v117, v122, v123
	v_cvt_pk_bf16_f32 v118, v124, v125
	v_cvt_pk_bf16_f32 v119, v126, v127
	global_store_dwordx4 v[128:129], v[116:119], off offset:256
	s_nop 1
	v_cvt_f32_ubyte1_e32 v119, v166
	v_cvt_f32_ubyte0_e32 v118, v166
	v_pk_add_f32 v[118:119], v[118:119], 0.5 op_sel_hi:[1,0]
	v_lshlrev_b64 v[116:117], 11, v[168:169]
	v_pk_mul_f32 v[118:119], v[118:119], s[86:87] op_sel_hi:[1,0]
	s_nop 0
	v_pk_mul_f32 v[112:113], v[112:113], v[118:119]
	v_cvt_f32_ubyte3_e32 v119, v166
	v_cvt_f32_ubyte2_e32 v118, v166
	v_pk_add_f32 v[118:119], v[118:119], 0.5 op_sel_hi:[1,0]
	s_nop 0
	v_pk_mul_f32 v[118:119], v[118:119], s[86:87] op_sel_hi:[1,0]
	s_nop 0
	v_pk_mul_f32 v[114:115], v[114:115], v[118:119]
	v_cvt_f32_ubyte1_e32 v119, v167
	v_cvt_f32_ubyte0_e32 v118, v167
	v_pk_add_f32 v[118:119], v[118:119], 0.5 op_sel_hi:[1,0]
	s_nop 0
	v_pk_mul_f32 v[118:119], v[118:119], s[86:87] op_sel_hi:[1,0]
	s_nop 0
	v_pk_mul_f32 v[118:119], v[108:109], v[118:119]
	v_cvt_f32_ubyte3_e32 v109, v167
	v_cvt_f32_ubyte2_e32 v108, v167
	v_pk_add_f32 v[108:109], v[108:109], 0.5 op_sel_hi:[1,0]
	s_nop 0
	v_pk_mul_f32 v[108:109], v[108:109], s[86:87] op_sel_hi:[1,0]
	s_nop 0
	v_pk_mul_f32 v[120:121], v[110:111], v[108:109]
	v_cvt_pk_bf16_f32 v108, v112, v113
	v_lshl_add_u64 v[112:113], s[8:9], 0, v[116:117]
	v_cvt_pk_bf16_f32 v109, v114, v115
	v_cvt_pk_bf16_f32 v110, v118, v119
	v_cvt_pk_bf16_f32 v111, v120, v121
	v_lshl_add_u64 v[112:113], v[112:113], 0, v[2:3]
	global_store_dwordx4 v[112:113], v[108:111], off
	s_nop 1
	v_cvt_f32_ubyte1_e32 v109, v164
	v_cvt_f32_ubyte0_e32 v108, v164
	v_pk_add_f32 v[108:109], v[108:109], 0.5 op_sel_hi:[1,0]
	s_nop 0
	v_pk_mul_f32 v[108:109], v[108:109], s[86:87] op_sel_hi:[1,0]
	s_nop 0
	v_pk_mul_f32 v[104:105], v[104:105], v[108:109]
	v_cvt_f32_ubyte3_e32 v109, v164
	v_cvt_f32_ubyte2_e32 v108, v164
	v_pk_add_f32 v[108:109], v[108:109], 0.5 op_sel_hi:[1,0]
	s_nop 0
	v_pk_mul_f32 v[108:109], v[108:109], s[86:87] op_sel_hi:[1,0]
	s_nop 0
	v_pk_mul_f32 v[106:107], v[106:107], v[108:109]
	v_cvt_f32_ubyte1_e32 v109, v165
	v_cvt_f32_ubyte0_e32 v108, v165
	v_pk_add_f32 v[108:109], v[108:109], 0.5 op_sel_hi:[1,0]
	s_nop 0
	v_pk_mul_f32 v[108:109], v[108:109], s[86:87] op_sel_hi:[1,0]
	s_nop 0
	v_pk_mul_f32 v[108:109], v[100:101], v[108:109]
	v_cvt_f32_ubyte3_e32 v101, v165
	v_cvt_f32_ubyte2_e32 v100, v165
	v_pk_add_f32 v[100:101], v[100:101], 0.5 op_sel_hi:[1,0]
	s_nop 0
	v_pk_mul_f32 v[100:101], v[100:101], s[86:87] op_sel_hi:[1,0]
	s_nop 0
	v_pk_mul_f32 v[110:111], v[102:103], v[100:101]
	v_cvt_pk_bf16_f32 v100, v104, v105
	v_cvt_pk_bf16_f32 v101, v106, v107
	v_cvt_pk_bf16_f32 v102, v108, v109
	v_cvt_pk_bf16_f32 v103, v110, v111
	global_store_dwordx4 v[112:113], v[100:103], off offset:256
	s_nop 1
	v_cvt_f32_ubyte1_e32 v103, v160
	v_cvt_f32_ubyte0_e32 v102, v160
	v_pk_add_f32 v[102:103], v[102:103], 0.5 op_sel_hi:[1,0]
	v_lshlrev_b64 v[100:101], 11, v[162:163]
	v_pk_mul_f32 v[102:103], v[102:103], s[86:87] op_sel_hi:[1,0]
	s_nop 0
	v_pk_mul_f32 v[96:97], v[96:97], v[102:103]
	v_cvt_f32_ubyte3_e32 v103, v160
	v_cvt_f32_ubyte2_e32 v102, v160
	v_pk_add_f32 v[102:103], v[102:103], 0.5 op_sel_hi:[1,0]
	s_nop 0
	v_pk_mul_f32 v[102:103], v[102:103], s[86:87] op_sel_hi:[1,0]
	s_nop 0
; __device__ __forceinline__ unsigned cvt_pk_bf16(float lo, float hi) { const f32x2_ v = {lo, hi}; return __builtin_bit_cast(unsigned, __builtin_convertvector(v, bf16x2_)); }
;     __device__ __forceinline__ void operator()(const f32x4 (&acc)[2][2][4][2], const Unit& u, int wr, int wc, int fr, int fq) const {
;     ...
; #pragma unroll
;             for (int m = 0; m < 4; ++m)
; #pragma unroll
;                 for (int bj = 0; bj < 2; ++bj) {
;                     const int row = row0 + ai * 128 + m * 16, c = c0 + bj * 128;
;                     float v[8];
; #pragma unroll
;                     for (int e = 0; e < 8; ++e) { const unsigned q = ((e < 4 ? gq[m][bj].x : gq[m][bj].y) >> (8 * (e & 3))) & 255u; v[e] = ((float)q + 0.5f) * (1.0f / 256.0f) * acc[ai][bj][m][e >> 2][e & 3]; }
;                     u32x4 w; w.x = cvt_pk_bf16(v[0], v[1]); w.y = cvt_pk_bf16(v[2], v[3]); w.z = cvt_pk_bf16(v[4], v[5]); w.w = cvt_pk_bf16(v[6], v[7]);
;                     *(u32x4*)(MG + (size_t)row * 1024 + c) = w;
;                 }
	v_pk_mul_f32 v[98:99], v[98:99], v[102:103]
	v_cvt_f32_ubyte1_e32 v103, v161
	v_cvt_f32_ubyte0_e32 v102, v161
	v_pk_add_f32 v[102:103], v[102:103], 0.5 op_sel_hi:[1,0]
	s_nop 0
	v_pk_mul_f32 v[102:103], v[102:103], s[86:87] op_sel_hi:[1,0]
	s_nop 0
	v_pk_mul_f32 v[102:103], v[92:93], v[102:103]
	v_cvt_f32_ubyte3_e32 v93, v161
	v_cvt_f32_ubyte2_e32 v92, v161
	v_pk_add_f32 v[92:93], v[92:93], 0.5 op_sel_hi:[1,0]
	s_nop 0
	v_pk_mul_f32 v[92:93], v[92:93], s[86:87] op_sel_hi:[1,0]
	s_nop 0
	v_pk_mul_f32 v[104:105], v[94:95], v[92:93]
	v_cvt_pk_bf16_f32 v92, v96, v97
	v_lshl_add_u64 v[96:97], s[8:9], 0, v[100:101]
	v_cvt_pk_bf16_f32 v93, v98, v99
	v_cvt_pk_bf16_f32 v94, v102, v103
	v_cvt_pk_bf16_f32 v95, v104, v105
	v_lshl_add_u64 v[96:97], v[96:97], 0, v[2:3]
	global_store_dwordx4 v[96:97], v[92:95], off
	s_nop 1
	v_cvt_f32_ubyte1_e32 v93, v158
	v_cvt_f32_ubyte0_e32 v92, v158
	v_pk_add_f32 v[92:93], v[92:93], 0.5 op_sel_hi:[1,0]
	s_nop 0
	v_pk_mul_f32 v[92:93], v[92:93], s[86:87] op_sel_hi:[1,0]
	s_nop 0
	v_pk_mul_f32 v[88:89], v[88:89], v[92:93]
	v_cvt_f32_ubyte3_e32 v93, v158
	v_cvt_f32_ubyte2_e32 v92, v158
	v_pk_add_f32 v[92:93], v[92:93], 0.5 op_sel_hi:[1,0]
	s_nop 0
	v_pk_mul_f32 v[92:93], v[92:93], s[86:87] op_sel_hi:[1,0]
	s_nop 0
	v_pk_mul_f32 v[90:91], v[90:91], v[92:93]
	v_cvt_f32_ubyte1_e32 v93, v159
	v_cvt_f32_ubyte0_e32 v92, v159
	v_pk_add_f32 v[92:93], v[92:93], 0.5 op_sel_hi:[1,0]
	s_nop 0
	v_pk_mul_f32 v[92:93], v[92:93], s[86:87] op_sel_hi:[1,0]
	s_nop 0
	v_pk_mul_f32 v[92:93], v[84:85], v[92:93]
	v_cvt_f32_ubyte3_e32 v85, v159
	v_cvt_f32_ubyte2_e32 v84, v159
	v_pk_add_f32 v[84:85], v[84:85], 0.5 op_sel_hi:[1,0]
	s_nop 0
	v_pk_mul_f32 v[84:85], v[84:85], s[86:87] op_sel_hi:[1,0]
	s_nop 0
	v_pk_mul_f32 v[94:95], v[86:87], v[84:85]
	v_cvt_pk_bf16_f32 v84, v88, v89
	v_cvt_pk_bf16_f32 v85, v90, v91
	v_cvt_pk_bf16_f32 v86, v92, v93
	v_cvt_pk_bf16_f32 v87, v94, v95
	global_store_dwordx4 v[96:97], v[84:87], off offset:256
	s_nop 1
	v_cvt_f32_ubyte1_e32 v87, v154
	v_cvt_f32_ubyte0_e32 v86, v154
	v_pk_add_f32 v[86:87], v[86:87], 0.5 op_sel_hi:[1,0]
	v_lshlrev_b64 v[84:85], 11, v[156:157]
	v_pk_mul_f32 v[86:87], v[86:87], s[86:87] op_sel_hi:[1,0]
	s_nop 0
	v_pk_mul_f32 v[80:81], v[80:81], v[86:87]
	v_cvt_f32_ubyte3_e32 v87, v154
	v_cvt_f32_ubyte2_e32 v86, v154
	v_pk_add_f32 v[86:87], v[86:87], 0.5 op_sel_hi:[1,0]
	s_nop 0
	v_pk_mul_f32 v[86:87], v[86:87], s[86:87] op_sel_hi:[1,0]
	s_nop 0
	v_pk_mul_f32 v[82:83], v[82:83], v[86:87]
	v_cvt_f32_ubyte1_e32 v87, v155
	v_cvt_f32_ubyte0_e32 v86, v155
	v_pk_add_f32 v[86:87], v[86:87], 0.5 op_sel_hi:[1,0]
	s_nop 0
	v_pk_mul_f32 v[86:87], v[86:87], s[86:87] op_sel_hi:[1,0]
	s_nop 0
	v_pk_mul_f32 v[86:87], v[76:77], v[86:87]
	v_cvt_f32_ubyte3_e32 v77, v155
	v_cvt_f32_ubyte2_e32 v76, v155
	v_pk_add_f32 v[76:77], v[76:77], 0.5 op_sel_hi:[1,0]
	s_nop 0
	v_pk_mul_f32 v[76:77], v[76:77], s[86:87] op_sel_hi:[1,0]
	s_nop 0
	v_pk_mul_f32 v[88:89], v[78:79], v[76:77]
	v_cvt_pk_bf16_f32 v76, v80, v81
	v_lshl_add_u64 v[80:81], s[8:9], 0, v[84:85]
	v_cvt_pk_bf16_f32 v77, v82, v83
	v_cvt_pk_bf16_f32 v78, v86, v87
	v_cvt_pk_bf16_f32 v79, v88, v89
	v_lshl_add_u64 v[80:81], v[80:81], 0, v[2:3]
	global_store_dwordx4 v[80:81], v[76:79], off
	s_nop 1
	v_cvt_f32_ubyte1_e32 v77, v152
	v_cvt_f32_ubyte0_e32 v76, v152
	v_pk_add_f32 v[76:77], v[76:77], 0.5 op_sel_hi:[1,0]
	s_nop 0
	v_pk_mul_f32 v[76:77], v[76:77], s[86:87] op_sel_hi:[1,0]
	s_nop 0
	v_pk_mul_f32 v[72:73], v[72:73], v[76:77]
	v_cvt_f32_ubyte3_e32 v77, v152
	v_cvt_f32_ubyte2_e32 v76, v152
	v_pk_add_f32 v[76:77], v[76:77], 0.5 op_sel_hi:[1,0]
	s_nop 0
	v_pk_mul_f32 v[76:77], v[76:77], s[86:87] op_sel_hi:[1,0]
	s_nop 0
	v_pk_mul_f32 v[74:75], v[74:75], v[76:77]
	v_cvt_f32_ubyte1_e32 v77, v153
	v_cvt_f32_ubyte0_e32 v76, v153
	v_pk_add_f32 v[76:77], v[76:77], 0.5 op_sel_hi:[1,0]
	s_nop 0
	v_pk_mul_f32 v[76:77], v[76:77], s[86:87] op_sel_hi:[1,0]
	s_nop 0
	v_pk_mul_f32 v[76:77], v[68:69], v[76:77]
	v_cvt_f32_ubyte3_e32 v69, v153
	v_cvt_f32_ubyte2_e32 v68, v153
	v_pk_add_f32 v[68:69], v[68:69], 0.5 op_sel_hi:[1,0]
	s_nop 0
	v_pk_mul_f32 v[68:69], v[68:69], s[86:87] op_sel_hi:[1,0]
	s_nop 0
	v_pk_mul_f32 v[78:79], v[70:71], v[68:69]
	v_cvt_pk_bf16_f32 v68, v72, v73
	v_cvt_pk_bf16_f32 v69, v74, v75
	v_cvt_pk_bf16_f32 v70, v76, v77
	v_cvt_pk_bf16_f32 v71, v78, v79
	global_store_dwordx4 v[80:81], v[68:71], off offset:256
	s_waitcnt vmcnt(0)
; __device__ __forceinline__ unsigned cvt_pk_bf16(float lo, float hi) { const f32x2_ v = {lo, hi}; return __builtin_bit_cast(unsigned, __builtin_convertvector(v, bf16x2_)); }
; __device__ __forceinline__ size_t g8_off(int row, int colg) { return ((size_t)(row >> 4) * 128 + (colg >> 5)) * 512 + (row & 15) * 32 + (colg & 31); }
;     __device__ __forceinline__ void operator()(const f32x4 (&acc)[2][2][4][2], const Unit& u, int wr, int wc, int fr, int fq) const {
;     ...
;         for (int ai = 0; ai < 2; ++ai) {
;             u32x2 gq[4][2];
; #pragma unroll
;             for (int m = 0; m < 4; ++m)
; #pragma unroll
;                 for (int bj = 0; bj < 2; ++bj) gq[m][bj] = *(const u32x2*)(G8 + g8_off(row0 + ai * 128 + m * 16, 3 * 1024 + c0 + bj * 128));
; #pragma unroll
;             for (int m = 0; m < 4; ++m)
; #pragma unroll
;                 for (int bj = 0; bj < 2; ++bj) {
;                     const int row = row0 + ai * 128 + m * 16, c = c0 + bj * 128;
;                     float v[8];
; #pragma unroll
;                     for (int e = 0; e < 8; ++e) { const unsigned q = ((e < 4 ? gq[m][bj].x : gq[m][bj].y) >> (8 * (e & 3))) & 255u; v[e] = ((float)q + 0.5f) * (1.0f / 256.0f) * acc[ai][bj][m][e >> 2][e & 3]; }
;                     u32x4 w; w.x = cvt_pk_bf16(v[0], v[1]); w.y = cvt_pk_bf16(v[2], v[3]); w.z = cvt_pk_bf16(v[4], v[5]); w.w = cvt_pk_bf16(v[6], v[7]);
;                     *(u32x4*)(MG + (size_t)row * 1024 + c) = w;
;                 }
	v_mov_b32_e32 v68, v202
	v_mov_b32_e32 v69, v203
	v_mov_b32_e32 v70, v204
	v_mov_b32_e32 v71, v205
	v_mov_b32_e32 v72, v228
	v_mov_b32_e32 v73, v229
	v_mov_b32_e32 v74, v226
	v_mov_b32_e32 v75, v227
	v_mov_b32_e32 v76, v224
	v_mov_b32_e32 v77, v225
	v_mov_b32_e32 v78, v222
	v_mov_b32_e32 v79, v223
	v_mov_b32_e32 v80, v214
	v_mov_b32_e32 v81, v215
	v_mov_b32_e32 v82, v212
	v_mov_b32_e32 v83, v213
	v_mov_b32_e32 v84, v210
	v_mov_b32_e32 v85, v211
	v_mov_b32_e32 v86, v200
	v_mov_b32_e32 v87, v201
	v_mov_b32_e32 v88, v206
	v_mov_b32_e32 v89, v207
	v_mov_b32_e32 v90, v208
	v_mov_b32_e32 v91, v209
	v_cvt_f32_ubyte1_e32 v93, v88
	v_cvt_f32_ubyte0_e32 v92, v88
	v_pk_add_f32 v[92:93], v[92:93], 0.5 op_sel_hi:[1,0]
	s_nop 0
	v_pk_mul_f32 v[92:93], v[92:93], s[86:87] op_sel_hi:[1,0]
	s_nop 0
	v_pk_mul_f32 v[64:65], v[64:65], v[92:93]
	v_cvt_f32_ubyte3_e32 v93, v88
	v_cvt_f32_ubyte2_e32 v92, v88
	v_pk_add_f32 v[92:93], v[92:93], 0.5 op_sel_hi:[1,0]
	s_nop 0
	v_pk_mul_f32 v[92:93], v[92:93], s[86:87] op_sel_hi:[1,0]
	s_nop 0
	v_pk_mul_f32 v[66:67], v[66:67], v[92:93]
	v_cvt_f32_ubyte1_e32 v93, v89
	v_cvt_f32_ubyte0_e32 v92, v89
	v_pk_add_f32 v[92:93], v[92:93], 0.5 op_sel_hi:[1,0]
	s_nop 0
	v_pk_mul_f32 v[92:93], v[92:93], s[86:87] op_sel_hi:[1,0]
	s_nop 0
	v_pk_mul_f32 v[92:93], v[60:61], v[92:93]
	v_cvt_f32_ubyte3_e32 v61, v89
	v_cvt_f32_ubyte2_e32 v60, v89
	v_pk_add_f32 v[60:61], v[60:61], 0.5 op_sel_hi:[1,0]
	s_nop 0
	v_pk_mul_f32 v[60:61], v[60:61], s[86:87] op_sel_hi:[1,0]
	s_nop 0
	v_pk_mul_f32 v[88:89], v[62:63], v[60:61]
	v_cvt_pk_bf16_f32 v60, v64, v65
	v_lshl_add_u64 v[64:65], s[8:9], 0, v[86:87]
	v_cvt_pk_bf16_f32 v61, v66, v67
	v_cvt_pk_bf16_f32 v62, v92, v93
	v_cvt_pk_bf16_f32 v63, v88, v89
	v_lshl_add_u64 v[64:65], v[64:65], 0, v[2:3]
	global_store_dwordx4 v[64:65], v[60:63], off
	s_nop 1
	v_cvt_f32_ubyte1_e32 v61, v90
	v_cvt_f32_ubyte0_e32 v60, v90
	v_pk_add_f32 v[60:61], v[60:61], 0.5 op_sel_hi:[1,0]
	s_nop 0
	v_pk_mul_f32 v[60:61], v[60:61], s[86:87] op_sel_hi:[1,0]
	s_nop 0
	v_pk_mul_f32 v[56:57], v[56:57], v[60:61]
	v_cvt_f32_ubyte3_e32 v61, v90
	v_cvt_f32_ubyte2_e32 v60, v90
	v_pk_add_f32 v[60:61], v[60:61], 0.5 op_sel_hi:[1,0]
	s_nop 0
	v_pk_mul_f32 v[60:61], v[60:61], s[86:87] op_sel_hi:[1,0]
	s_nop 0
	v_pk_mul_f32 v[58:59], v[58:59], v[60:61]
	v_cvt_f32_ubyte1_e32 v61, v91
	v_cvt_f32_ubyte0_e32 v60, v91
	v_pk_add_f32 v[60:61], v[60:61], 0.5 op_sel_hi:[1,0]
	s_nop 0
	v_pk_mul_f32 v[60:61], v[60:61], s[86:87] op_sel_hi:[1,0]
	s_nop 0
	v_pk_mul_f32 v[60:61], v[52:53], v[60:61]
	v_cvt_f32_ubyte3_e32 v53, v91
	v_cvt_f32_ubyte2_e32 v52, v91
	v_pk_add_f32 v[52:53], v[52:53], 0.5 op_sel_hi:[1,0]
	s_nop 0
	v_pk_mul_f32 v[52:53], v[52:53], s[86:87] op_sel_hi:[1,0]
	s_nop 0
	v_pk_mul_f32 v[62:63], v[54:55], v[52:53]
	v_cvt_pk_bf16_f32 v52, v56, v57
	v_cvt_pk_bf16_f32 v53, v58, v59
	v_cvt_pk_bf16_f32 v54, v60, v61
	v_cvt_pk_bf16_f32 v55, v62, v63
	global_store_dwordx4 v[64:65], v[52:55], off offset:256
	s_nop 1
	v_cvt_f32_ubyte1_e32 v55, v82
	v_cvt_f32_ubyte0_e32 v54, v82
	v_pk_add_f32 v[54:55], v[54:55], 0.5 op_sel_hi:[1,0]
	v_lshlrev_b64 v[52:53], 11, v[84:85]
	v_pk_mul_f32 v[54:55], v[54:55], s[86:87] op_sel_hi:[1,0]
	s_nop 0
	v_pk_mul_f32 v[48:49], v[48:49], v[54:55]
	v_cvt_f32_ubyte3_e32 v55, v82
	v_cvt_f32_ubyte2_e32 v54, v82
	v_pk_add_f32 v[54:55], v[54:55], 0.5 op_sel_hi:[1,0]
	s_nop 0
	v_pk_mul_f32 v[54:55], v[54:55], s[86:87] op_sel_hi:[1,0]
	s_nop 0
	v_pk_mul_f32 v[50:51], v[50:51], v[54:55]
	v_cvt_f32_ubyte1_e32 v55, v83
	v_cvt_f32_ubyte0_e32 v54, v83
	v_pk_add_f32 v[54:55], v[54:55], 0.5 op_sel_hi:[1,0]
	s_nop 0
	v_pk_mul_f32 v[54:55], v[54:55], s[86:87] op_sel_hi:[1,0]
	s_nop 0
	v_pk_mul_f32 v[54:55], v[44:45], v[54:55]
	v_cvt_f32_ubyte3_e32 v45, v83
	v_cvt_f32_ubyte2_e32 v44, v83
	v_pk_add_f32 v[44:45], v[44:45], 0.5 op_sel_hi:[1,0]
	s_nop 0
	v_pk_mul_f32 v[44:45], v[44:45], s[86:87] op_sel_hi:[1,0]
	s_nop 0
	v_pk_mul_f32 v[56:57], v[46:47], v[44:45]
	v_cvt_pk_bf16_f32 v44, v48, v49
	v_lshl_add_u64 v[48:49], s[8:9], 0, v[52:53]
	v_cvt_pk_bf16_f32 v45, v50, v51
	v_cvt_pk_bf16_f32 v46, v54, v55
	v_cvt_pk_bf16_f32 v47, v56, v57
	v_lshl_add_u64 v[48:49], v[48:49], 0, v[2:3]
	global_store_dwordx4 v[48:49], v[44:47], off
	s_nop 1
	v_cvt_f32_ubyte1_e32 v45, v80
	v_cvt_f32_ubyte0_e32 v44, v80
	v_pk_add_f32 v[44:45], v[44:45], 0.5 op_sel_hi:[1,0]
	s_nop 0
	v_pk_mul_f32 v[44:45], v[44:45], s[86:87] op_sel_hi:[1,0]
	s_nop 0
	v_pk_mul_f32 v[40:41], v[40:41], v[44:45]
	v_cvt_f32_ubyte3_e32 v45, v80
	v_cvt_f32_ubyte2_e32 v44, v80
	v_pk_add_f32 v[44:45], v[44:45], 0.5 op_sel_hi:[1,0]
	s_nop 0
	v_pk_mul_f32 v[44:45], v[44:45], s[86:87] op_sel_hi:[1,0]
	s_nop 0
	v_pk_mul_f32 v[42:43], v[42:43], v[44:45]
	v_cvt_f32_ubyte1_e32 v45, v81
	v_cvt_f32_ubyte0_e32 v44, v81
	v_pk_add_f32 v[44:45], v[44:45], 0.5 op_sel_hi:[1,0]
	s_nop 0
	v_pk_mul_f32 v[44:45], v[44:45], s[86:87] op_sel_hi:[1,0]
	s_nop 0
	v_pk_mul_f32 v[44:45], v[36:37], v[44:45]
	v_cvt_f32_ubyte3_e32 v37, v81
	v_cvt_f32_ubyte2_e32 v36, v81
	v_pk_add_f32 v[36:37], v[36:37], 0.5 op_sel_hi:[1,0]
	s_nop 0
	v_pk_mul_f32 v[36:37], v[36:37], s[86:87] op_sel_hi:[1,0]
; __device__ __forceinline__ unsigned cvt_pk_bf16(float lo, float hi) { const f32x2_ v = {lo, hi}; return __builtin_bit_cast(unsigned, __builtin_convertvector(v, bf16x2_)); }
; template <class Epi, class Sched>
; __device__ __forceinline__ void gemm_phase(LAS unsigned char* lds, const Gemm g, const Sched& S, const Epi& E) {
;     ...
;         E(acc, cur, wr, wc, fr, fq);
;         if (!has_next) break;
; #pragma unroll
;         for (int a = 0; a < 2; ++a)
; #pragma unroll
;             for (int b = 0; b < 2; ++b)
; #pragma unroll
;                 for (int m = 0; m < 4; ++m)
; #pragma unroll
;                     for (int n = 0; n < 2; ++n) acc[a][b][m][n] = (f32x4){0.f, 0.f, 0.f, 0.f};
;         cur = nxt; cA = nA; cB = nB; ++ui;
;     __device__ __forceinline__ void operator()(const f32x4 (&acc)[2][2][4][2], const Unit& u, int wr, int wc, int fr, int fq) const {
;     ...
; #pragma unroll
;             for (int m = 0; m < 4; ++m)
; #pragma unroll
;                 for (int bj = 0; bj < 2; ++bj) {
;                     const int row = row0 + ai * 128 + m * 16, c = c0 + bj * 128;
;                     float v[8];
; #pragma unroll
;                     for (int e = 0; e < 8; ++e) { const unsigned q = ((e < 4 ? gq[m][bj].x : gq[m][bj].y) >> (8 * (e & 3))) & 255u; v[e] = ((float)q + 0.5f) * (1.0f / 256.0f) * acc[ai][bj][m][e >> 2][e & 3]; }
;                     u32x4 w; w.x = cvt_pk_bf16(v[0], v[1]); w.y = cvt_pk_bf16(v[2], v[3]); w.z = cvt_pk_bf16(v[4], v[5]); w.w = cvt_pk_bf16(v[6], v[7]);
;                     *(u32x4*)(MG + (size_t)row * 1024 + c) = w;
;                 }
;             __builtin_amdgcn_sched_barrier(0);
	s_nop 0
	v_pk_mul_f32 v[46:47], v[38:39], v[36:37]
	v_cvt_pk_bf16_f32 v36, v40, v41
	v_cvt_pk_bf16_f32 v37, v42, v43
	v_cvt_pk_bf16_f32 v38, v44, v45
	v_cvt_pk_bf16_f32 v39, v46, v47
	global_store_dwordx4 v[48:49], v[36:39], off offset:256
	s_nop 1
	v_cvt_f32_ubyte1_e32 v39, v76
	v_cvt_f32_ubyte0_e32 v38, v76
	v_pk_add_f32 v[38:39], v[38:39], 0.5 op_sel_hi:[1,0]
	v_lshlrev_b64 v[36:37], 11, v[78:79]
	v_pk_mul_f32 v[38:39], v[38:39], s[86:87] op_sel_hi:[1,0]
	s_nop 0
	v_pk_mul_f32 v[32:33], v[32:33], v[38:39]
	v_cvt_f32_ubyte3_e32 v39, v76
	v_cvt_f32_ubyte2_e32 v38, v76
	v_pk_add_f32 v[38:39], v[38:39], 0.5 op_sel_hi:[1,0]
	s_nop 0
	v_pk_mul_f32 v[38:39], v[38:39], s[86:87] op_sel_hi:[1,0]
	s_nop 0
	v_pk_mul_f32 v[34:35], v[34:35], v[38:39]
	v_cvt_f32_ubyte1_e32 v39, v77
	v_cvt_f32_ubyte0_e32 v38, v77
	v_pk_add_f32 v[38:39], v[38:39], 0.5 op_sel_hi:[1,0]
	s_nop 0
	v_pk_mul_f32 v[38:39], v[38:39], s[86:87] op_sel_hi:[1,0]
	s_nop 0
	v_pk_mul_f32 v[38:39], v[28:29], v[38:39]
	v_cvt_f32_ubyte3_e32 v29, v77
	v_cvt_f32_ubyte2_e32 v28, v77
	v_pk_add_f32 v[28:29], v[28:29], 0.5 op_sel_hi:[1,0]
	s_nop 0
	v_pk_mul_f32 v[28:29], v[28:29], s[86:87] op_sel_hi:[1,0]
	s_nop 0
	v_pk_mul_f32 v[40:41], v[30:31], v[28:29]
	v_cvt_pk_bf16_f32 v28, v32, v33
	v_lshl_add_u64 v[32:33], s[8:9], 0, v[36:37]
	v_cvt_pk_bf16_f32 v29, v34, v35
	v_cvt_pk_bf16_f32 v30, v38, v39
	v_cvt_pk_bf16_f32 v31, v40, v41
	v_lshl_add_u64 v[32:33], v[32:33], 0, v[2:3]
	global_store_dwordx4 v[32:33], v[28:31], off
	s_nop 1
	v_cvt_f32_ubyte1_e32 v29, v70
	v_cvt_f32_ubyte0_e32 v28, v70
	v_pk_add_f32 v[28:29], v[28:29], 0.5 op_sel_hi:[1,0]
	s_nop 0
	v_pk_mul_f32 v[28:29], v[28:29], s[86:87] op_sel_hi:[1,0]
	s_nop 0
	v_pk_mul_f32 v[24:25], v[24:25], v[28:29]
	v_cvt_f32_ubyte3_e32 v29, v70
	v_cvt_f32_ubyte2_e32 v28, v70
	v_pk_add_f32 v[28:29], v[28:29], 0.5 op_sel_hi:[1,0]
	s_nop 0
	v_pk_mul_f32 v[28:29], v[28:29], s[86:87] op_sel_hi:[1,0]
	s_nop 0
	v_pk_mul_f32 v[26:27], v[26:27], v[28:29]
	v_cvt_f32_ubyte1_e32 v29, v71
	v_cvt_f32_ubyte0_e32 v28, v71
	v_pk_add_f32 v[28:29], v[28:29], 0.5 op_sel_hi:[1,0]
	s_nop 0
	v_pk_mul_f32 v[28:29], v[28:29], s[86:87] op_sel_hi:[1,0]
	s_nop 0
	v_pk_mul_f32 v[28:29], v[20:21], v[28:29]
	v_cvt_f32_ubyte3_e32 v21, v71
	v_cvt_f32_ubyte2_e32 v20, v71
	v_pk_add_f32 v[20:21], v[20:21], 0.5 op_sel_hi:[1,0]
	s_nop 0
	v_pk_mul_f32 v[20:21], v[20:21], s[86:87] op_sel_hi:[1,0]
	s_nop 0
	v_pk_mul_f32 v[30:31], v[22:23], v[20:21]
	v_cvt_pk_bf16_f32 v20, v24, v25
	v_cvt_pk_bf16_f32 v21, v26, v27
	v_cvt_pk_bf16_f32 v22, v28, v29
	v_cvt_pk_bf16_f32 v23, v30, v31
	global_store_dwordx4 v[32:33], v[20:23], off offset:256
	s_nop 1
	v_cvt_f32_ubyte1_e32 v23, v72
	v_cvt_f32_ubyte0_e32 v22, v72
	v_pk_add_f32 v[22:23], v[22:23], 0.5 op_sel_hi:[1,0]
	v_lshlrev_b64 v[20:21], 11, v[74:75]
	v_pk_mul_f32 v[22:23], v[22:23], s[86:87] op_sel_hi:[1,0]
	s_nop 0
	v_pk_mul_f32 v[16:17], v[16:17], v[22:23]
	v_cvt_f32_ubyte3_e32 v23, v72
	v_cvt_f32_ubyte2_e32 v22, v72
	v_pk_add_f32 v[22:23], v[22:23], 0.5 op_sel_hi:[1,0]
	s_nop 0
	v_pk_mul_f32 v[22:23], v[22:23], s[86:87] op_sel_hi:[1,0]
	s_nop 0
	v_pk_mul_f32 v[18:19], v[18:19], v[22:23]
	v_cvt_f32_ubyte1_e32 v23, v73
	v_cvt_f32_ubyte0_e32 v22, v73
	v_pk_add_f32 v[22:23], v[22:23], 0.5 op_sel_hi:[1,0]
	s_nop 0
	v_pk_mul_f32 v[22:23], v[22:23], s[86:87] op_sel_hi:[1,0]
	s_nop 0
	v_pk_mul_f32 v[22:23], v[12:13], v[22:23]
	v_cvt_f32_ubyte3_e32 v13, v73
	v_cvt_f32_ubyte2_e32 v12, v73
	v_pk_add_f32 v[12:13], v[12:13], 0.5 op_sel_hi:[1,0]
	s_nop 0
	v_pk_mul_f32 v[12:13], v[12:13], s[86:87] op_sel_hi:[1,0]
	s_nop 0
	v_pk_mul_f32 v[24:25], v[14:15], v[12:13]
	v_cvt_pk_bf16_f32 v12, v16, v17
	v_lshl_add_u64 v[16:17], s[8:9], 0, v[20:21]
	v_lshl_add_u64 v[16:17], v[16:17], 0, v[2:3]
	v_cvt_f32_ubyte1_e32 v3, v68
	v_cvt_f32_ubyte0_e32 v2, v68
	v_pk_add_f32 v[2:3], v[2:3], 0.5 op_sel_hi:[1,0]
	v_cvt_pk_bf16_f32 v13, v18, v19
	v_pk_mul_f32 v[2:3], v[2:3], s[86:87] op_sel_hi:[1,0]
	v_cvt_pk_bf16_f32 v14, v22, v23
	v_pk_mul_f32 v[2:3], v[8:9], v[2:3]
	v_cvt_f32_ubyte3_e32 v9, v68
	v_cvt_f32_ubyte2_e32 v8, v68
	v_pk_add_f32 v[8:9], v[8:9], 0.5 op_sel_hi:[1,0]
	v_cvt_pk_bf16_f32 v15, v24, v25
	v_pk_mul_f32 v[8:9], v[8:9], s[86:87] op_sel_hi:[1,0]
	v_cvt_pk_bf16_f32 v2, v2, v3
	v_pk_mul_f32 v[8:9], v[10:11], v[8:9]
	v_cvt_f32_ubyte1_e32 v11, v69
	v_cvt_f32_ubyte0_e32 v10, v69
	v_pk_add_f32 v[10:11], v[10:11], 0.5 op_sel_hi:[1,0]
	v_cvt_pk_bf16_f32 v3, v8, v9
	v_pk_mul_f32 v[10:11], v[10:11], s[86:87] op_sel_hi:[1,0]
	global_store_dwordx4 v[16:17], v[12:15], off
	v_pk_mul_f32 v[4:5], v[4:5], v[10:11]
	v_cvt_f32_ubyte3_e32 v11, v69
	v_cvt_f32_ubyte2_e32 v10, v69
	v_pk_add_f32 v[10:11], v[10:11], 0.5 op_sel_hi:[1,0]
	v_cvt_pk_bf16_f32 v4, v4, v5
	v_pk_mul_f32 v[10:11], v[10:11], s[86:87] op_sel_hi:[1,0]
	s_nop 0
	v_pk_mul_f32 v[6:7], v[6:7], v[10:11]
	s_nop 0
	v_cvt_pk_bf16_f32 v5, v6, v7
	global_store_dwordx4 v[16:17], v[2:5], off offset:256
	s_and_b64 vcc, exec, s[4:5]
	s_mov_b32 s3, s10
	s_mov_b32 s2, s12
	s_mov_b64 s[18:19], s[16:17]
	s_mov_b64 s[20:21], s[14:15]
	s_cbranch_vccnz .LBB0_47
